# phase0 KC/VCT bf16 cache conversion: 16 loads batched, one wait, then cvt+stores (was load/wait/cvt/store chain)
# speedup vs baseline: 1.0042x; 1.0042x over previous
.LBB0_109:
	s_cmpk_lt_i32 s38, 0x1a80
	s_cbranch_scc1 .LBB0_108
	s_cmpk_lg_i32 s38, 0x1b80
	s_mov_b64 s[0:1], -1
	s_cbranch_scc0 .LBB0_130
	s_add_i32 s2, s38, 0xffffe580
	v_lshlrev_b32_e32 v81, 1, v128
	s_cmp_gt_u32 s2, 0x7f
	s_cbranch_scc1 .Lkcv_vct
	s_lshr_b32 s0, s2, 6
	s_lshl_b32 s0, s0, 18
	s_and_b32 s1, s2, 7
	s_lshl_b32 s1, s1, 15
	s_or_b32 s0, s0, s1
	s_bfe_u32 s1, s2, 0x30003
	s_lshl_b32 s1, s1, 7
	s_or_b32 s0, s0, s1
	s_lshl_b32 s0, s0, 2
	s_add_u32 s98, s80, s0
	s_addc_u32 s99, s81, 0
	v_lshrrev_b32_e32 v80, 7, v128
	v_lshlrev_b32_e32 v80, 10, v80
	v_and_b32_e32 v82, 0x7f, v128
	v_or_b32_e32 v80, v80, v82
	v_lshlrev_b32_e32 v80, 2, v80
	s_lshl_b32 s0, s2, 13
	s_add_u32 s100, s70, s0
	s_addc_u32 s101, s71, 0
	global_load_dword v64, v80, s[98:99]
	s_add_u32 s98, s98, 0x2000
	s_addc_u32 s99, s99, 0
	global_load_dword v65, v80, s[98:99]
	s_add_u32 s98, s98, 0x2000
	s_addc_u32 s99, s99, 0
	global_load_dword v66, v80, s[98:99]
	s_add_u32 s98, s98, 0x2000
	s_addc_u32 s99, s99, 0
	global_load_dword v67, v80, s[98:99]
	s_add_u32 s98, s98, 0x2000
	s_addc_u32 s99, s99, 0
	global_load_dword v68, v80, s[98:99]
	s_add_u32 s98, s98, 0x2000
	s_addc_u32 s99, s99, 0
	global_load_dword v69, v80, s[98:99]
	s_add_u32 s98, s98, 0x2000
	s_addc_u32 s99, s99, 0
	global_load_dword v70, v80, s[98:99]
	s_add_u32 s98, s98, 0x2000
	s_addc_u32 s99, s99, 0
	global_load_dword v71, v80, s[98:99]
	s_add_u32 s98, s98, 0x2000
	s_addc_u32 s99, s99, 0
	global_load_dword v72, v80, s[98:99]
	s_add_u32 s98, s98, 0x2000
	s_addc_u32 s99, s99, 0
	global_load_dword v73, v80, s[98:99]
	s_add_u32 s98, s98, 0x2000
	s_addc_u32 s99, s99, 0
	global_load_dword v74, v80, s[98:99]
	s_add_u32 s98, s98, 0x2000
	s_addc_u32 s99, s99, 0
	global_load_dword v75, v80, s[98:99]
	s_add_u32 s98, s98, 0x2000
	s_addc_u32 s99, s99, 0
	global_load_dword v76, v80, s[98:99]
	s_add_u32 s98, s98, 0x2000
	s_addc_u32 s99, s99, 0
	global_load_dword v77, v80, s[98:99]
	s_add_u32 s98, s98, 0x2000
	s_addc_u32 s99, s99, 0
	global_load_dword v78, v80, s[98:99]
	s_add_u32 s98, s98, 0x2000
	s_addc_u32 s99, s99, 0
	global_load_dword v79, v80, s[98:99]
	s_branch .Lkcv_cvt
.Lkcv_vct:
	s_addk_i32 s2, 0xff80
	s_lshr_b32 s0, s2, 6
	s_lshl_b32 s0, s0, 18
	s_and_b32 s1, s2, 7
	s_lshl_b32 s1, s1, 4
	s_or_b32 s0, s0, s1
	s_bfe_u32 s1, s2, 0x30003
	s_lshl_b32 s1, s1, 7
	s_or_b32 s0, s0, s1
	s_lshl_b32 s0, s0, 2
	s_add_u32 s98, s82, s0
	s_addc_u32 s99, s83, 0
	v_lshlrev_b32_e32 v80, 12, v128
	s_lshl_b32 s0, s2, 13
	s_add_u32 s100, s68, s0
	s_addc_u32 s101, s69, 0
	global_load_dwordx4 v[64:67], v80, s[98:99]
	global_load_dwordx4 v[68:71], v80, s[98:99] offset:16
	global_load_dwordx4 v[72:75], v80, s[98:99] offset:32
	global_load_dwordx4 v[76:79], v80, s[98:99] offset:48
.Lkcv_cvt:
	s_waitcnt vmcnt(0)
	v_cvt_pk_bf16_f32 v64, v64, v64
	v_cvt_pk_bf16_f32 v65, v65, v65
	v_cvt_pk_bf16_f32 v66, v66, v66
	v_cvt_pk_bf16_f32 v67, v67, v67
	v_cvt_pk_bf16_f32 v68, v68, v68
	v_cvt_pk_bf16_f32 v69, v69, v69
	v_cvt_pk_bf16_f32 v70, v70, v70
	v_cvt_pk_bf16_f32 v71, v71, v71
	v_cvt_pk_bf16_f32 v72, v72, v72
	v_cvt_pk_bf16_f32 v73, v73, v73
	v_cvt_pk_bf16_f32 v74, v74, v74
	v_cvt_pk_bf16_f32 v75, v75, v75
	v_cvt_pk_bf16_f32 v76, v76, v76
	v_cvt_pk_bf16_f32 v77, v77, v77
	v_cvt_pk_bf16_f32 v78, v78, v78
	v_cvt_pk_bf16_f32 v79, v79, v79
	global_store_short v81, v64, s[100:101]
	global_store_short v81, v65, s[100:101] offset:512
	global_store_short v81, v66, s[100:101] offset:1024
	global_store_short v81, v67, s[100:101] offset:1536
	global_store_short v81, v68, s[100:101] offset:2048
	global_store_short v81, v69, s[100:101] offset:2560
	global_store_short v81, v70, s[100:101] offset:3072
	global_store_short v81, v71, s[100:101] offset:3584
	s_add_u32 s100, s100, 0x1000
	s_addc_u32 s101, s101, 0
	global_store_short v81, v72, s[100:101]
	global_store_short v81, v73, s[100:101] offset:512
	global_store_short v81, v74, s[100:101] offset:1024
	global_store_short v81, v75, s[100:101] offset:1536
	global_store_short v81, v76, s[100:101] offset:2048
	global_store_short v81, v77, s[100:101] offset:2560
	global_store_short v81, v78, s[100:101] offset:3072
	global_store_short v81, v79, s[100:101] offset:3584
